# norm phases: two row groups per loop trip, second group's loads (renamed registers) issued before the first group's reductions and stores; original body kept as fallback
# baseline (speedup 1.0000x reference)
; #define BIDX (opaque_bid() * 2 + HALF_)
; __device__ __forceinline__ void phase_norm(const Params& p, int mode, const u16* D, const float* gD, float scale,
;                            const float* gH, bool writeH) {
;     ...
;   for (int it = BIDX; it < T_TOK / 8; it += VGRID) {
;     const int row0 = it * 8 + wave * 2;
;     float4 xv[2][4], dv[2][4], g1[4], g2[4];
; #pragma unroll
;     for (int r = 0; r < 2; ++r)
; #pragma unroll
;       for (int i = 0; i < 4; ++i) {
;         xv[r][i] = *(const float4*)(xsrc + (size_t)(row0 + r) * DM + i * 256 + lane * 4);
;         if (mode == 1) {
;           const uint2 w = *(const uint2*)(D + (size_t)(row0 + r) * DM + i * 256 + lane * 4);
;           dv[r][i] = make_float4(__uint_as_float(w.x << 16), __uint_as_float(w.x & 0xffff0000u),
;                                  __uint_as_float(w.y << 16), __uint_as_float(w.y & 0xffff0000u));
;         } else {
;           dv[r][i] = make_float4(0.f, 0.f, 0.f, 0.f);
;         }
;       }
; #pragma unroll
;     for (int i = 0; i < 4; ++i) {
;       g1[i] = (mode == 1) ? *(const float4*)(gD + i * 256 + lane * 4) : make_float4(0.f, 0.f, 0.f, 0.f);
;       g2[i] = writeH ? *(const float4*)(gH + i * 256 + lane * 4) : make_float4(0.f, 0.f, 0.f, 0.f);
.LBB0_495:
	s_add_i32 s99, s10, s96
	s_cmpk_lt_i32 s99, 0x800
	s_cbranch_scc0 .Lnorm_single
	v_ashrrev_i32_e32 v79, 31, v78
	v_add_u32_e32 v22, 1, v78
	v_lshlrev_b64 v[84:85], 12, v[78:79]
	v_lshlrev_b64 v[80:81], 11, v[78:79]
	v_ashrrev_i32_e32 v23, 31, v22
	v_cndmask_b32_e64 v0, 0, 1, s[24:25]
	v_lshlrev_b64 v[86:87], 12, v[22:23]
	v_lshlrev_b64 v[82:83], 11, v[22:23]
	v_cmp_ne_u32_e64 s[40:41], 1, v0
	v_cndmask_b32_e64 v0, 0, 1, s[20:21]
	v_lshl_add_u64 v[122:123], v[66:67], 0, v[84:85]
	v_lshl_add_u64 v[124:125], v[68:69], 0, v[80:81]
	v_cmp_ne_u32_e64 s[38:39], 1, v0
	v_lshl_add_u64 v[126:127], v[66:67], 0, v[86:87]
	v_lshl_add_u64 v[128:129], v[68:69], 0, v[82:83]
	s_and_b64 vcc, exec, s[40:41]
	s_cbranch_vccnz .Lnorm_nog1a
	global_load_dwordx4 v[50:53], v[70:71], off
	global_load_dwordx4 v[54:57], v[70:71], off offset:1024
	global_load_dwordx4 v[58:61], v[70:71], off offset:2048
	global_load_dwordx4 v[62:65], v[70:71], off offset:3072

; __device__ __forceinline__ void phase_norm(const Params& p, int mode, const u16* D, const float* gD, float scale,
;                            const float* gH, bool writeH) {
;     ...
;     float4 xv[2][4], dv[2][4], g1[4], g2[4];
; #pragma unroll
;     for (int r = 0; r < 2; ++r)
; #pragma unroll
;       for (int i = 0; i < 4; ++i) {
;         xv[r][i] = *(const float4*)(xsrc + (size_t)(row0 + r) * DM + i * 256 + lane * 4);
;         if (mode == 1) {
;           const uint2 w = *(const uint2*)(D + (size_t)(row0 + r) * DM + i * 256 + lane * 4);
;           dv[r][i] = make_float4(__uint_as_float(w.x << 16), __uint_as_float(w.x & 0xffff0000u),
;                                  __uint_as_float(w.y << 16), __uint_as_float(w.y & 0xffff0000u));
;         } else {
;           dv[r][i] = make_float4(0.f, 0.f, 0.f, 0.f);
;         }
;       }
; #pragma unroll
;     for (int i = 0; i < 4; ++i) {
;       g1[i] = (mode == 1) ? *(const float4*)(gD + i * 256 + lane * 4) : make_float4(0.f, 0.f, 0.f, 0.f);
;       g2[i] = writeH ? *(const float4*)(gH + i * 256 + lane * 4) : make_float4(0.f, 0.f, 0.f, 0.f);
;     }
;     __builtin_amdgcn_sched_barrier(0);
;     if (mode == 1) {
;       float ss0 = 0.f, ss1 = 0.f;
; #pragma unroll
;       for (int i = 0; i < 4; ++i) {
;         ss0 += dv[0][i].x * dv[0][i].x + dv[0][i].y * dv[0][i].y + dv[0][i].z * dv[0][i].z + dv[0][i].w * dv[0][i].w;
;         ss1 += dv[1][i].x * dv[1][i].x + dv[1][i].y * dv[1][i].y + dv[1][i].z * dv[1][i].z + dv[1][i].w * dv[1][i].w;
;       }
; #pragma unroll
;       for (int o = 32; o; o >>= 1) { ss0 += __shfl_xor(ss0, o); ss1 += __shfl_xor(ss1, o); }
.Lnorm_noda:
	global_load_dwordx4 v[2:5], v[122:123], off
	global_load_dwordx4 v[6:9], v[122:123], off offset:1024
	global_load_dwordx4 v[10:13], v[122:123], off offset:2048
	global_load_dwordx4 v[14:17], v[122:123], off offset:3072
	global_load_dwordx4 v[18:21], v[126:127], off
	global_load_dwordx4 v[22:25], v[126:127], off offset:1024
	global_load_dwordx4 v[26:29], v[126:127], off offset:2048
	global_load_dwordx4 v[30:33], v[126:127], off offset:3072
	v_add_u32_e32 v234, s11, v78
	v_ashrrev_i32_e32 v235, 31, v234
	v_add_u32_e32 v152, 1, v234
	v_lshlrev_b64 v[240:241], 12, v[234:235]
	v_lshlrev_b64 v[236:237], 11, v[234:235]
	v_ashrrev_i32_e32 v153, 31, v152
	v_cndmask_b32_e64 v228, 0, 1, s[24:25]
	v_lshlrev_b64 v[242:243], 12, v[152:153]
	v_lshlrev_b64 v[238:239], 11, v[152:153]
	v_cmp_ne_u32_e64 s[40:41], 1, v228
	v_cndmask_b32_e64 v228, 0, 1, s[20:21]
	v_lshl_add_u64 v[192:193], v[66:67], 0, v[240:241]
	v_lshl_add_u64 v[194:195], v[68:69], 0, v[236:237]
	v_cmp_ne_u32_e64 s[38:39], 1, v228
	v_lshl_add_u64 v[196:197], v[66:67], 0, v[242:243]
	v_lshl_add_u64 v[198:199], v[68:69], 0, v[238:239]
	s_and_b64 vcc, exec, s[40:41]
	s_cbranch_vccnz .Lnorm_nog1b
	global_load_dwordx4 v[204:207], v[70:71], off
	global_load_dwordx4 v[208:211], v[70:71], off offset:1024
	global_load_dwordx4 v[212:215], v[70:71], off offset:2048
	global_load_dwordx4 v[216:219], v[70:71], off offset:3072
.Lnorm_nog1b:
	s_and_b64 vcc, exec, s[38:39]
	s_cbranch_vccnz .Lnorm_nog2b
	global_load_dwordx4 v[176:179], v[72:73], off
	global_load_dwordx4 v[180:183], v[72:73], off offset:1024
	global_load_dwordx4 v[184:187], v[72:73], off offset:2048
	global_load_dwordx4 v[188:191], v[72:73], off offset:3072
.Lnorm_nog2b:
	s_and_b64 vcc, exec, s[40:41]
	s_cbranch_vccnz .Lnorm_nodb
	global_load_dwordx2 v[164:165], v[194:195], off
	global_load_dwordx2 v[166:167], v[194:195], off offset:512
	global_load_dwordx2 v[168:169], v[194:195], off offset:1024
	global_load_dwordx2 v[170:171], v[194:195], off offset:1536
	global_load_dwordx2 v[220:221], v[198:199], off
	global_load_dwordx2 v[222:223], v[198:199], off offset:512
	global_load_dwordx2 v[224:225], v[198:199], off offset:1024
	global_load_dwordx2 v[226:227], v[198:199], off offset:1536
.Lnorm_nodb:
	global_load_dwordx4 v[132:135], v[192:193], off
	global_load_dwordx4 v[136:139], v[192:193], off offset:1024
	global_load_dwordx4 v[140:143], v[192:193], off offset:2048
	global_load_dwordx4 v[144:147], v[192:193], off offset:3072
	global_load_dwordx4 v[148:151], v[196:197], off
	global_load_dwordx4 v[152:155], v[196:197], off offset:1024
	global_load_dwordx4 v[156:159], v[196:197], off offset:2048
	global_load_dwordx4 v[160:163], v[196:197], off offset:3072
.Ln527a:
	s_and_b64 vcc, exec, s[24:25]
	s_cbranch_vccz .Ln529a
	s_waitcnt vmcnt(16)
	v_lshlrev_b32_e32 v90, 16, v93
	v_and_b32_e32 v91, 0xffff0000, v93
	v_and_b32_e32 v93, 0xffff0000, v92
	v_lshlrev_b32_e32 v92, 16, v92
	v_lshlrev_b32_e32 v88, 16, v95
	v_and_b32_e32 v89, 0xffff0000, v95
	v_and_b32_e32 v95, 0xffff0000, v94
	v_lshlrev_b32_e32 v94, 16, v94
	v_lshlrev_b32_e32 v98, 16, v101
	v_and_b32_e32 v99, 0xffff0000, v101
	v_and_b32_e32 v101, 0xffff0000, v100
	v_lshlrev_b32_e32 v100, 16, v100
	v_lshlrev_b32_e32 v96, 16, v103
	v_and_b32_e32 v97, 0xffff0000, v103
	v_and_b32_e32 v103, 0xffff0000, v102
	v_lshlrev_b32_e32 v102, 16, v102
	v_lshlrev_b32_e32 v106, 16, v109
	v_and_b32_e32 v107, 0xffff0000, v109
	v_and_b32_e32 v109, 0xffff0000, v108
	v_lshlrev_b32_e32 v108, 16, v108
	v_lshlrev_b32_e32 v104, 16, v111
	v_and_b32_e32 v105, 0xffff0000, v111
	v_and_b32_e32 v111, 0xffff0000, v110
	v_lshlrev_b32_e32 v110, 16, v110
	v_lshlrev_b32_e32 v114, 16, v117
	v_and_b32_e32 v115, 0xffff0000, v117
	v_and_b32_e32 v117, 0xffff0000, v116
	v_lshlrev_b32_e32 v116, 16, v116
	v_lshlrev_b32_e32 v112, 16, v119
	v_and_b32_e32 v113, 0xffff0000, v119
	v_and_b32_e32 v119, 0xffff0000, v118
	v_lshlrev_b32_e32 v118, 16, v118
	v_mov_b32_e32 v122, v92
	v_mov_b32_e32 v123, v94
	v_pk_mul_f32 v[122:123], v[122:123], v[122:123]
	v_mov_b32_e32 v124, v93
	v_mov_b32_e32 v125, v95
	v_pk_fma_f32 v[122:123], v[124:125], v[124:125], v[122:123]
	v_mov_b32_e32 v124, v90
	v_mov_b32_e32 v125, v88
	v_pk_fma_f32 v[122:123], v[124:125], v[124:125], v[122:123]
	v_mov_b32_e32 v124, v91
	v_mov_b32_e32 v125, v89
	v_pk_fma_f32 v[122:123], v[124:125], v[124:125], v[122:123]
	v_mov_b32_e32 v124, v108
	v_mov_b32_e32 v125, v110
	v_pk_mul_f32 v[124:125], v[124:125], v[124:125]
	v_mov_b32_e32 v126, v109
	v_mov_b32_e32 v127, v111
	v_pk_fma_f32 v[124:125], v[126:127], v[126:127], v[124:125]
	v_mov_b32_e32 v126, v106
	v_mov_b32_e32 v127, v104
	v_pk_fma_f32 v[124:125], v[126:127], v[126:127], v[124:125]
	v_mov_b32_e32 v126, v107
	v_mov_b32_e32 v127, v105
	v_pk_fma_f32 v[124:125], v[126:127], v[126:127], v[124:125]
	v_mov_b32_e32 v126, v100
	v_mov_b32_e32 v127, v102
	v_pk_mul_f32 v[126:127], v[126:127], v[126:127]
	v_mov_b32_e32 v128, v101
	v_mov_b32_e32 v129, v103
	v_pk_fma_f32 v[126:127], v[128:129], v[128:129], v[126:127]
	v_mov_b32_e32 v128, v98
	v_mov_b32_e32 v129, v96
	v_pk_fma_f32 v[126:127], v[128:129], v[128:129], v[126:127]
	v_mov_b32_e32 v128, v99
	v_mov_b32_e32 v129, v97
	v_pk_fma_f32 v[126:127], v[128:129], v[128:129], v[126:127]
	v_mov_b32_e32 v128, v116
	v_mov_b32_e32 v129, v118
	v_pk_mul_f32 v[128:129], v[128:129], v[128:129]
	v_mov_b32_e32 v130, v117
	v_mov_b32_e32 v131, v119
	v_pk_fma_f32 v[128:129], v[130:131], v[130:131], v[128:129]
	v_mov_b32_e32 v130, v114
	v_mov_b32_e32 v131, v112
	v_pk_fma_f32 v[128:129], v[130:131], v[130:131], v[128:129]
	v_mov_b32_e32 v130, v115
	v_mov_b32_e32 v131, v113
	v_and_b32_e32 v0, 64, v202
	v_pk_fma_f32 v[128:129], v[130:131], v[130:131], v[128:129]
	v_add_u32_e32 v0, 64, v0
	v_xor_b32_e32 v79, 32, v202
	v_mov_b32_e32 v130, v124
	v_mov_b32_e32 v131, v122
	v_mov_b32_e32 v122, v125
	v_cmp_lt_i32_e32 vcc, v79, v0
	v_pk_add_f32 v[122:123], v[130:131], v[122:123]
	v_mov_b32_e32 v124, v128
	v_mov_b32_e32 v125, v126
	v_cndmask_b32_e32 v79, v202, v79, vcc
	v_pk_add_f32 v[122:123], v[122:123], v[124:125]
	v_mov_b32_e32 v126, v129
	v_lshlrev_b32_e32 v79, 2, v79
	v_pk_add_f32 v[122:123], v[122:123], v[126:127]
	ds_bpermute_b32 v125, v79, v123
	ds_bpermute_b32 v124, v79, v122
	v_xor_b32_e32 v79, 16, v202
	v_cmp_lt_i32_e32 vcc, v79, v0
	s_waitcnt lgkmcnt(0)
; __device__ __forceinline__ void phase_norm(const Params& p, int mode, const u16* D, const float* gD, float scale,
;                            const float* gH, bool writeH) {
;     ...
;       for (int o = 32; o; o >>= 1) { ss0 += __shfl_xor(ss0, o); ss1 += __shfl_xor(ss1, o); }
;       const float r0 = rsqrtf(ss0 * (1.0f / DM) + EPSN) * scale;
;       const float r1 = rsqrtf(ss1 * (1.0f / DM) + EPSN) * scale;
; #pragma unroll
;       for (int i = 0; i < 4; ++i) {
;         xv[0][i].x += dv[0][i].x * r0 * g1[i].x; xv[0][i].y += dv[0][i].y * r0 * g1[i].y;
;         xv[0][i].z += dv[0][i].z * r0 * g1[i].z; xv[0][i].w += dv[0][i].w * r0 * g1[i].w;
;         xv[1][i].x += dv[1][i].x * r1 * g1[i].x; xv[1][i].y += dv[1][i].y * r1 * g1[i].y;
;         xv[1][i].z += dv[1][i].z * r1 * g1[i].z; xv[1][i].w += dv[1][i].w * r1 * g1[i].w;
;       }
;     }
; #pragma unroll
;     for (int r = 0; r < 2; ++r)
; #pragma unroll
;       for (int i = 0; i < 4; ++i) *(float4*)(p.x + (size_t)(row0 + r) * DM + i * 256 + lane * 4) = xv[r][i];
	v_pk_add_f32 v[122:123], v[122:123], v[124:125]
	v_cndmask_b32_e32 v79, v202, v79, vcc
	v_lshlrev_b32_e32 v79, 2, v79
	ds_bpermute_b32 v125, v79, v123
	ds_bpermute_b32 v124, v79, v122
	v_xor_b32_e32 v79, 8, v202
	v_cmp_lt_i32_e32 vcc, v79, v0
	s_waitcnt lgkmcnt(0)
	v_pk_add_f32 v[122:123], v[122:123], v[124:125]
	v_cndmask_b32_e32 v79, v202, v79, vcc
	v_lshlrev_b32_e32 v79, 2, v79
	ds_bpermute_b32 v125, v79, v123
	ds_bpermute_b32 v124, v79, v122
	v_xor_b32_e32 v79, 4, v202
	v_cmp_lt_i32_e32 vcc, v79, v0
	s_waitcnt lgkmcnt(0)
	v_pk_add_f32 v[122:123], v[122:123], v[124:125]
	v_cndmask_b32_e32 v79, v202, v79, vcc
	v_lshlrev_b32_e32 v79, 2, v79
	ds_bpermute_b32 v125, v79, v123
	ds_bpermute_b32 v124, v79, v122
	v_xor_b32_e32 v79, 2, v202
	v_cmp_lt_i32_e32 vcc, v79, v0
	s_waitcnt lgkmcnt(0)
	v_pk_add_f32 v[122:123], v[122:123], v[124:125]
	v_cndmask_b32_e32 v79, v202, v79, vcc
	v_lshlrev_b32_e32 v79, 2, v79
	ds_bpermute_b32 v125, v79, v123
	ds_bpermute_b32 v124, v79, v122
	v_xor_b32_e32 v79, 1, v202
	v_cmp_lt_i32_e32 vcc, v79, v0
	s_waitcnt lgkmcnt(0)
	v_pk_add_f32 v[122:123], v[122:123], v[124:125]
	v_cndmask_b32_e32 v0, v202, v79, vcc
	v_lshlrev_b32_e32 v0, 2, v0
	ds_bpermute_b32 v125, v0, v123
	ds_bpermute_b32 v124, v0, v122
	s_waitcnt lgkmcnt(0)
	v_pk_add_f32 v[122:123], v[122:123], v[124:125]
	s_nop 0
	v_pk_fma_f32 v[122:123], v[122:123], s[22:23], v[174:175] op_sel_hi:[1,0,0]
	s_nop 0
	v_mul_f32_e32 v0, 0x4b800000, v123
	v_cmp_gt_f32_e32 vcc, s56, v123
	v_mul_f32_e32 v79, 0x4b800000, v122
	v_cmp_gt_f32_e64 s[0:1], s56, v122
	v_cndmask_b32_e32 v0, v123, v0, vcc
	v_rsq_f32_e32 v0, v0
	v_cndmask_b32_e64 v79, v122, v79, s[0:1]
	v_rsq_f32_e32 v79, v79
	v_mul_f32_e32 v121, 0x45800000, v0
	v_cndmask_b32_e32 v0, v0, v121, vcc
	v_mul_f32_e32 v121, 0x45800000, v79
	v_mul_f32_e32 v0, v120, v0
	v_cndmask_b32_e64 v79, v79, v121, s[0:1]
	v_mul_f32_e32 v122, v120, v79
	v_pk_mul_f32 v[90:91], v[90:91], v[0:1] op_sel_hi:[1,0]
	v_pk_mul_f32 v[92:93], v[92:93], v[0:1] op_sel_hi:[1,0]
	s_waitcnt vmcnt(8)
	v_pk_fma_f32 v[4:5], v[52:53], v[90:91], v[4:5]
	v_pk_mul_f32 v[90:91], v[108:109], v[122:123] op_sel_hi:[1,0]
	v_pk_fma_f32 v[2:3], v[50:51], v[92:93], v[2:3]
	v_pk_fma_f32 v[18:19], v[50:51], v[90:91], v[18:19]
	v_pk_mul_f32 v[50:51], v[106:107], v[122:123] op_sel_hi:[1,0]
	s_nop 0
	v_pk_fma_f32 v[20:21], v[52:53], v[50:51], v[20:21]
	v_pk_mul_f32 v[50:51], v[94:95], v[0:1] op_sel_hi:[1,0]
	s_nop 0
	v_pk_fma_f32 v[6:7], v[54:55], v[50:51], v[6:7]
	v_pk_mul_f32 v[50:51], v[88:89], v[0:1] op_sel_hi:[1,0]
	s_nop 0
	v_pk_fma_f32 v[8:9], v[56:57], v[50:51], v[8:9]
	v_pk_mul_f32 v[50:51], v[110:111], v[122:123] op_sel_hi:[1,0]
	s_nop 0
	v_pk_fma_f32 v[22:23], v[54:55], v[50:51], v[22:23]
	v_pk_mul_f32 v[50:51], v[104:105], v[122:123] op_sel_hi:[1,0]
	s_nop 0
	v_pk_fma_f32 v[24:25], v[56:57], v[50:51], v[24:25]
	v_pk_mul_f32 v[50:51], v[100:101], v[0:1] op_sel_hi:[1,0]
	s_nop 0
	v_pk_fma_f32 v[10:11], v[58:59], v[50:51], v[10:11]
	v_pk_mul_f32 v[50:51], v[98:99], v[0:1] op_sel_hi:[1,0]
	s_nop 0
	v_pk_fma_f32 v[12:13], v[60:61], v[50:51], v[12:13]
	v_pk_mul_f32 v[50:51], v[116:117], v[122:123] op_sel_hi:[1,0]
	s_nop 0
	v_pk_fma_f32 v[26:27], v[58:59], v[50:51], v[26:27]
	v_pk_mul_f32 v[50:51], v[114:115], v[122:123] op_sel_hi:[1,0]
	s_nop 0
	v_pk_fma_f32 v[28:29], v[60:61], v[50:51], v[28:29]
	v_pk_mul_f32 v[50:51], v[102:103], v[0:1] op_sel_hi:[1,0]
	s_nop 0
	v_pk_fma_f32 v[14:15], v[62:63], v[50:51], v[14:15]
	v_pk_mul_f32 v[50:51], v[96:97], v[0:1] op_sel_hi:[1,0]
	s_nop 0
	v_pk_fma_f32 v[16:17], v[64:65], v[50:51], v[16:17]
	v_pk_mul_f32 v[50:51], v[118:119], v[122:123] op_sel_hi:[1,0]
	s_nop 0
	v_pk_fma_f32 v[30:31], v[62:63], v[50:51], v[30:31]
	v_pk_mul_f32 v[50:51], v[112:113], v[122:123] op_sel_hi:[1,0]
	s_nop 0
	v_pk_fma_f32 v[32:33], v[64:65], v[50:51], v[32:33]
.Ln529a:
	s_waitcnt vmcnt(8)
	v_lshl_add_u64 v[50:51], v[76:77], 0, v[84:85]
	global_store_dwordx4 v[50:51], v[2:5], off
	global_store_dwordx4 v[50:51], v[6:9], off offset:1024
	global_store_dwordx4 v[50:51], v[10:13], off offset:2048
	global_store_dwordx4 v[50:51], v[14:17], off offset:3072
	v_lshl_add_u64 v[50:51], v[76:77], 0, v[86:87]
	s_and_b64 vcc, exec, s[38:39]
	global_store_dwordx4 v[50:51], v[18:21], off
	global_store_dwordx4 v[50:51], v[22:25], off offset:1024
	global_store_dwordx4 v[50:51], v[26:29], off offset:2048
	global_store_dwordx4 v[50:51], v[30:33], off offset:3072
	s_cbranch_vccnz .LnBcomp
; __device__ __forceinline__ void phase_norm(const Params& p, int mode, const u16* D, const float* gD, float scale,
;                            const float* gH, bool writeH) {
;     ...
;     if (writeH) {
;       float ss0 = 0.f, ss1 = 0.f;
; #pragma unroll
;       for (int i = 0; i < 4; ++i) {
;         ss0 += xv[0][i].x * xv[0][i].x + xv[0][i].y * xv[0][i].y + xv[0][i].z * xv[0][i].z + xv[0][i].w * xv[0][i].w;
;         ss1 += xv[1][i].x * xv[1][i].x + xv[1][i].y * xv[1][i].y + xv[1][i].z * xv[1][i].z + xv[1][i].w * xv[1][i].w;
;       }
; #pragma unroll
;       for (int o = 32; o; o >>= 1) { ss0 += __shfl_xor(ss0, o); ss1 += __shfl_xor(ss1, o); }
;       const float rr[2] = {rsqrtf(ss0 * (1.0f / DM) + EPSN), rsqrtf(ss1 * (1.0f / DM) + EPSN)};
; #pragma unroll
;       for (int r = 0; r < 2; ++r)
; #pragma unroll
;         for (int i = 0; i < 4; ++i) {
;           uint2 o;
;           o.x = pack2bf(xv[r][i].x * rr[r] * g2[i].x, xv[r][i].y * rr[r] * g2[i].y);
;           o.y = pack2bf(xv[r][i].z * rr[r] * g2[i].z, xv[r][i].w * rr[r] * g2[i].w);
;           *(uint2*)(H + (size_t)(row0 + r) * DM + i * 256 + lane * 4) = o;
;         }
	v_mov_b32_e32 v52, v3
	v_mov_b32_e32 v53, v7
	v_mov_b32_e32 v50, v2
	v_mov_b32_e32 v51, v6
	v_pk_mul_f32 v[52:53], v[52:53], v[52:53]
	v_mov_b32_e32 v54, v19
	v_pk_fma_f32 v[50:51], v[50:51], v[50:51], v[52:53]
	v_mov_b32_e32 v52, v4
	v_mov_b32_e32 v53, v8
	v_pk_fma_f32 v[50:51], v[52:53], v[52:53], v[50:51]
	v_mov_b32_e32 v52, v5
	v_mov_b32_e32 v53, v9
	v_mov_b32_e32 v55, v23
	v_pk_fma_f32 v[50:51], v[52:53], v[52:53], v[50:51]
	v_mov_b32_e32 v52, v18
	v_mov_b32_e32 v53, v22
	v_pk_mul_f32 v[54:55], v[54:55], v[54:55]
	v_mov_b32_e32 v56, v11
	v_pk_fma_f32 v[52:53], v[52:53], v[52:53], v[54:55]
	v_mov_b32_e32 v54, v20
	v_mov_b32_e32 v55, v24
	v_pk_fma_f32 v[52:53], v[54:55], v[54:55], v[52:53]
	v_mov_b32_e32 v54, v21
	v_mov_b32_e32 v55, v25
	v_mov_b32_e32 v57, v15
	v_pk_fma_f32 v[52:53], v[54:55], v[54:55], v[52:53]
	v_mov_b32_e32 v54, v10
	v_mov_b32_e32 v55, v14
	v_pk_mul_f32 v[56:57], v[56:57], v[56:57]
	v_mov_b32_e32 v58, v27
	v_pk_fma_f32 v[54:55], v[54:55], v[54:55], v[56:57]
	v_mov_b32_e32 v56, v12
	v_mov_b32_e32 v57, v16
	v_pk_fma_f32 v[54:55], v[56:57], v[56:57], v[54:55]
	v_mov_b32_e32 v56, v13
	v_mov_b32_e32 v57, v17
	v_mov_b32_e32 v59, v31
	v_pk_fma_f32 v[54:55], v[56:57], v[56:57], v[54:55]
	v_mov_b32_e32 v56, v26
	v_mov_b32_e32 v57, v30
	v_pk_mul_f32 v[58:59], v[58:59], v[58:59]
	v_and_b32_e32 v0, 64, v202
	v_pk_fma_f32 v[56:57], v[56:57], v[56:57], v[58:59]
	v_mov_b32_e32 v58, v28
	v_mov_b32_e32 v59, v32
	v_pk_fma_f32 v[56:57], v[58:59], v[58:59], v[56:57]
	v_mov_b32_e32 v58, v29
	v_mov_b32_e32 v59, v33
	v_pk_fma_f32 v[56:57], v[58:59], v[58:59], v[56:57]
	v_add_u32_e32 v0, 64, v0
	v_xor_b32_e32 v58, 32, v202
	v_cmp_lt_i32_e32 vcc, v58, v0
	v_mov_b32_e32 v59, v50
	v_mov_b32_e32 v50, v53
	v_cndmask_b32_e32 v58, v202, v58, vcc
	v_lshlrev_b32_e32 v60, 2, v58
	v_mov_b32_e32 v58, v52
	v_pk_add_f32 v[50:51], v[58:59], v[50:51]
	v_mov_b32_e32 v52, v56
	v_mov_b32_e32 v53, v54
	v_pk_add_f32 v[50:51], v[50:51], v[52:53]
	v_mov_b32_e32 v54, v57
	v_pk_add_f32 v[50:51], v[50:51], v[54:55]
	ds_bpermute_b32 v53, v60, v51
	ds_bpermute_b32 v52, v60, v50
	v_xor_b32_e32 v54, 16, v202
	v_cmp_lt_i32_e32 vcc, v54, v0
	s_waitcnt lgkmcnt(0)
	v_pk_add_f32 v[50:51], v[50:51], v[52:53]
	v_cndmask_b32_e32 v54, v202, v54, vcc
	v_lshlrev_b32_e32 v54, 2, v54
	ds_bpermute_b32 v53, v54, v51
	ds_bpermute_b32 v52, v54, v50
	v_xor_b32_e32 v54, 8, v202
	v_cmp_lt_i32_e32 vcc, v54, v0
	s_waitcnt lgkmcnt(0)
	v_pk_add_f32 v[50:51], v[50:51], v[52:53]
	v_cndmask_b32_e32 v54, v202, v54, vcc
	v_lshlrev_b32_e32 v54, 2, v54
	ds_bpermute_b32 v53, v54, v51
	ds_bpermute_b32 v52, v54, v50
	v_xor_b32_e32 v54, 4, v202
	v_cmp_lt_i32_e32 vcc, v54, v0
	s_waitcnt lgkmcnt(0)
	v_pk_add_f32 v[50:51], v[50:51], v[52:53]
	v_cndmask_b32_e32 v54, v202, v54, vcc
	v_lshlrev_b32_e32 v54, 2, v54
	ds_bpermute_b32 v53, v54, v51
	ds_bpermute_b32 v52, v54, v50
	v_xor_b32_e32 v54, 2, v202
	v_cmp_lt_i32_e32 vcc, v54, v0
	s_waitcnt lgkmcnt(0)
	v_pk_add_f32 v[50:51], v[50:51], v[52:53]
	v_cndmask_b32_e32 v54, v202, v54, vcc
	v_lshlrev_b32_e32 v54, 2, v54
	ds_bpermute_b32 v53, v54, v51
	ds_bpermute_b32 v52, v54, v50
	v_xor_b32_e32 v54, 1, v202
	v_cmp_lt_i32_e32 vcc, v54, v0
	s_waitcnt lgkmcnt(0)
	v_pk_add_f32 v[50:51], v[50:51], v[52:53]
	v_cndmask_b32_e32 v0, v202, v54, vcc
	v_lshlrev_b32_e32 v0, 2, v0
	ds_bpermute_b32 v53, v0, v51
	ds_bpermute_b32 v52, v0, v50
	s_waitcnt lgkmcnt(0)
	v_pk_add_f32 v[50:51], v[50:51], v[52:53]
	s_nop 0
	v_pk_fma_f32 v[50:51], v[50:51], s[22:23], v[174:175] op_sel_hi:[1,0,0]
	v_lshl_add_u64 v[52:53], v[74:75], 0, v[80:81]
	v_mul_f32_e32 v0, 0x4b800000, v51
	v_cmp_gt_f32_e32 vcc, s56, v51
	v_cmp_gt_f32_e64 s[0:1], s56, v50
	s_nop 0
	v_cndmask_b32_e32 v0, v51, v0, vcc
	v_rsq_f32_e32 v0, v0
	v_mul_f32_e32 v51, 0x4b800000, v50
	v_cndmask_b32_e64 v50, v50, v51, s[0:1]
	v_rsq_f32_e32 v50, v50
	v_mul_f32_e32 v51, 0x45800000, v0
	v_cndmask_b32_e32 v0, v0, v51, vcc
	v_pk_mul_f32 v[2:3], v[2:3], v[0:1] op_sel_hi:[1,0]
	v_pk_mul_f32 v[4:5], v[4:5], v[0:1] op_sel_hi:[1,0]
	v_pk_mul_f32 v[2:3], v[34:35], v[2:3]
	v_pk_mul_f32 v[4:5], v[36:37], v[4:5]
	v_cvt_pk_bf16_f32 v2, v2, v3
	v_cvt_pk_bf16_f32 v3, v4, v5
	global_store_dwordx2 v[52:53], v[2:3], off
	v_pk_mul_f32 v[2:3], v[6:7], v[0:1] op_sel_hi:[1,0]
	v_pk_mul_f32 v[4:5], v[8:9], v[0:1] op_sel_hi:[1,0]
	v_pk_mul_f32 v[2:3], v[38:39], v[2:3]
	v_pk_mul_f32 v[4:5], v[40:41], v[4:5]
	v_cvt_pk_bf16_f32 v2, v2, v3
	v_cvt_pk_bf16_f32 v3, v4, v5
	global_store_dwordx2 v[52:53], v[2:3], off offset:512
	v_pk_mul_f32 v[2:3], v[10:11], v[0:1] op_sel_hi:[1,0]
	v_pk_mul_f32 v[4:5], v[12:13], v[0:1] op_sel_hi:[1,0]
	v_pk_mul_f32 v[2:3], v[42:43], v[2:3]
	v_pk_mul_f32 v[4:5], v[44:45], v[4:5]
	v_cvt_pk_bf16_f32 v2, v2, v3
	v_cvt_pk_bf16_f32 v3, v4, v5
	v_mul_f32_e32 v51, 0x45800000, v50
	global_store_dwordx2 v[52:53], v[2:3], off offset:1024
	v_pk_mul_f32 v[2:3], v[14:15], v[0:1] op_sel_hi:[1,0]
	v_pk_mul_f32 v[4:5], v[16:17], v[0:1] op_sel_hi:[1,0]
	v_cndmask_b32_e64 v50, v50, v51, s[0:1]
	v_pk_mul_f32 v[2:3], v[46:47], v[2:3]
	v_pk_mul_f32 v[4:5], v[48:49], v[4:5]
	v_cvt_pk_bf16_f32 v2, v2, v3
	v_cvt_pk_bf16_f32 v3, v4, v5
	v_pk_mul_f32 v[4:5], v[18:19], v[50:51] op_sel_hi:[1,0]
	v_pk_mul_f32 v[6:7], v[20:21], v[50:51] op_sel_hi:[1,0]
	v_pk_mul_f32 v[4:5], v[34:35], v[4:5]
	v_pk_mul_f32 v[6:7], v[36:37], v[6:7]
	global_store_dwordx2 v[52:53], v[2:3], off offset:1536
	v_lshl_add_u64 v[2:3], v[74:75], 0, v[82:83]
	v_cvt_pk_bf16_f32 v4, v4, v5
	v_cvt_pk_bf16_f32 v5, v6, v7
	global_store_dwordx2 v[2:3], v[4:5], off
	v_pk_mul_f32 v[4:5], v[22:23], v[50:51] op_sel_hi:[1,0]
	v_pk_mul_f32 v[6:7], v[24:25], v[50:51] op_sel_hi:[1,0]
	v_pk_mul_f32 v[4:5], v[38:39], v[4:5]
	v_pk_mul_f32 v[6:7], v[40:41], v[6:7]
	v_cvt_pk_bf16_f32 v4, v4, v5
	v_cvt_pk_bf16_f32 v5, v6, v7
	global_store_dwordx2 v[2:3], v[4:5], off offset:512
	v_pk_mul_f32 v[4:5], v[26:27], v[50:51] op_sel_hi:[1,0]
	v_pk_mul_f32 v[6:7], v[28:29], v[50:51] op_sel_hi:[1,0]
	v_pk_mul_f32 v[4:5], v[42:43], v[4:5]
	v_pk_mul_f32 v[6:7], v[44:45], v[6:7]
	v_cvt_pk_bf16_f32 v4, v4, v5
	v_cvt_pk_bf16_f32 v5, v6, v7
	global_store_dwordx2 v[2:3], v[4:5], off offset:1024
	v_pk_mul_f32 v[4:5], v[30:31], v[50:51] op_sel_hi:[1,0]
	v_pk_mul_f32 v[6:7], v[32:33], v[50:51] op_sel_hi:[1,0]
	v_pk_mul_f32 v[4:5], v[46:47], v[4:5]
	v_pk_mul_f32 v[6:7], v[48:49], v[6:7]
	v_cvt_pk_bf16_f32 v4, v4, v5
	v_cvt_pk_bf16_f32 v5, v6, v7
	global_store_dwordx2 v[2:3], v[4:5], off offset:1536
	s_branch .LnBcomp
; __device__ __forceinline__ void phase_norm(const Params& p, int mode, const u16* D, const float* gD, float scale,
;                            const float* gH, bool writeH) {
;     ...
;     if (mode == 1) {
;       float ss0 = 0.f, ss1 = 0.f;
; #pragma unroll
;       for (int i = 0; i < 4; ++i) {
;         ss0 += dv[0][i].x * dv[0][i].x + dv[0][i].y * dv[0][i].y + dv[0][i].z * dv[0][i].z + dv[0][i].w * dv[0][i].w;
;         ss1 += dv[1][i].x * dv[1][i].x + dv[1][i].y * dv[1][i].y + dv[1][i].z * dv[1][i].z + dv[1][i].w * dv[1][i].w;
;       }
; #pragma unroll
;       for (int o = 32; o; o >>= 1) { ss0 += __shfl_xor(ss0, o); ss1 += __shfl_xor(ss1, o); }
;       const float r0 = rsqrtf(ss0 * (1.0f / DM) + EPSN) * scale;
;       const float r1 = rsqrtf(ss1 * (1.0f / DM) + EPSN) * scale;
.LnBcomp:
.Ln527b:
	s_and_b64 vcc, exec, s[24:25]
	s_cbranch_vccz .Ln529b
	s_waitcnt vmcnt(16)
	v_lshlrev_b32_e32 v90, 16, v165
	v_and_b32_e32 v91, 0xffff0000, v165
	v_and_b32_e32 v165, 0xffff0000, v164
	v_lshlrev_b32_e32 v164, 16, v164
	v_lshlrev_b32_e32 v88, 16, v167
	v_and_b32_e32 v89, 0xffff0000, v167
	v_and_b32_e32 v167, 0xffff0000, v166
	v_lshlrev_b32_e32 v166, 16, v166
	v_lshlrev_b32_e32 v98, 16, v169
	v_and_b32_e32 v99, 0xffff0000, v169
	v_and_b32_e32 v169, 0xffff0000, v168
	v_lshlrev_b32_e32 v168, 16, v168
	v_lshlrev_b32_e32 v96, 16, v171
	v_and_b32_e32 v97, 0xffff0000, v171
	v_and_b32_e32 v171, 0xffff0000, v170
	v_lshlrev_b32_e32 v170, 16, v170
	v_lshlrev_b32_e32 v106, 16, v221
	v_and_b32_e32 v107, 0xffff0000, v221
	v_and_b32_e32 v221, 0xffff0000, v220
	v_lshlrev_b32_e32 v220, 16, v220
	v_lshlrev_b32_e32 v104, 16, v223
	v_and_b32_e32 v105, 0xffff0000, v223
	v_and_b32_e32 v223, 0xffff0000, v222
	v_lshlrev_b32_e32 v222, 16, v222
	v_lshlrev_b32_e32 v114, 16, v225
	v_and_b32_e32 v115, 0xffff0000, v225
	v_and_b32_e32 v225, 0xffff0000, v224
	v_lshlrev_b32_e32 v224, 16, v224
	v_lshlrev_b32_e32 v112, 16, v227
	v_and_b32_e32 v113, 0xffff0000, v227
	v_and_b32_e32 v227, 0xffff0000, v226
	v_lshlrev_b32_e32 v226, 16, v226
	v_mov_b32_e32 v192, v164
	v_mov_b32_e32 v193, v166
	v_pk_mul_f32 v[192:193], v[192:193], v[192:193]
	v_mov_b32_e32 v194, v165
	v_mov_b32_e32 v195, v167
	v_pk_fma_f32 v[192:193], v[194:195], v[194:195], v[192:193]
	v_mov_b32_e32 v194, v90
	v_mov_b32_e32 v195, v88
	v_pk_fma_f32 v[192:193], v[194:195], v[194:195], v[192:193]
	v_mov_b32_e32 v194, v91
	v_mov_b32_e32 v195, v89
	v_pk_fma_f32 v[192:193], v[194:195], v[194:195], v[192:193]
	v_mov_b32_e32 v194, v220
	v_mov_b32_e32 v195, v222
	v_pk_mul_f32 v[194:195], v[194:195], v[194:195]
	v_mov_b32_e32 v196, v221
	v_mov_b32_e32 v197, v223
	v_pk_fma_f32 v[194:195], v[196:197], v[196:197], v[194:195]
	v_mov_b32_e32 v196, v106
	v_mov_b32_e32 v197, v104
	v_pk_fma_f32 v[194:195], v[196:197], v[196:197], v[194:195]
	v_mov_b32_e32 v196, v107
	v_mov_b32_e32 v197, v105
	v_pk_fma_f32 v[194:195], v[196:197], v[196:197], v[194:195]
	v_mov_b32_e32 v196, v168
	v_mov_b32_e32 v197, v170
	v_pk_mul_f32 v[196:197], v[196:197], v[196:197]
	v_mov_b32_e32 v198, v169
	v_mov_b32_e32 v199, v171
	v_pk_fma_f32 v[196:197], v[198:199], v[198:199], v[196:197]
	v_mov_b32_e32 v198, v98
	v_mov_b32_e32 v199, v96
	v_pk_fma_f32 v[196:197], v[198:199], v[198:199], v[196:197]
	v_mov_b32_e32 v198, v99
	v_mov_b32_e32 v199, v97
	v_pk_fma_f32 v[196:197], v[198:199], v[198:199], v[196:197]
	v_mov_b32_e32 v198, v224
	v_mov_b32_e32 v199, v226
	v_pk_mul_f32 v[198:199], v[198:199], v[198:199]
	v_mov_b32_e32 v130, v225
	v_mov_b32_e32 v131, v227
	v_pk_fma_f32 v[198:199], v[130:131], v[130:131], v[198:199]
	v_mov_b32_e32 v130, v114
	v_mov_b32_e32 v131, v112
	v_pk_fma_f32 v[198:199], v[130:131], v[130:131], v[198:199]
	v_mov_b32_e32 v130, v115
	v_mov_b32_e32 v131, v113
	v_and_b32_e32 v228, 64, v202
	v_pk_fma_f32 v[198:199], v[130:131], v[130:131], v[198:199]
	v_add_u32_e32 v228, 64, v228
	v_xor_b32_e32 v235, 32, v202
	v_mov_b32_e32 v130, v194
	v_mov_b32_e32 v131, v192
	v_mov_b32_e32 v192, v195
	v_cmp_lt_i32_e32 vcc, v235, v228
	v_pk_add_f32 v[192:193], v[130:131], v[192:193]
	v_mov_b32_e32 v194, v198
	v_mov_b32_e32 v195, v196
	v_cndmask_b32_e32 v235, v202, v235, vcc
	v_pk_add_f32 v[192:193], v[192:193], v[194:195]
	v_mov_b32_e32 v196, v199
	v_lshlrev_b32_e32 v235, 2, v235
	v_pk_add_f32 v[192:193], v[192:193], v[196:197]
	ds_bpermute_b32 v195, v235, v193
	ds_bpermute_b32 v194, v235, v192
	v_xor_b32_e32 v235, 16, v202
	v_cmp_lt_i32_e32 vcc, v235, v228
	s_waitcnt lgkmcnt(0)
	v_pk_add_f32 v[192:193], v[192:193], v[194:195]
	v_cndmask_b32_e32 v235, v202, v235, vcc
	v_lshlrev_b32_e32 v235, 2, v235
	ds_bpermute_b32 v195, v235, v193
	ds_bpermute_b32 v194, v235, v192
	v_xor_b32_e32 v235, 8, v202
	v_cmp_lt_i32_e32 vcc, v235, v228
	s_waitcnt lgkmcnt(0)
	v_pk_add_f32 v[192:193], v[192:193], v[194:195]
	v_cndmask_b32_e32 v235, v202, v235, vcc
	v_lshlrev_b32_e32 v235, 2, v235
	ds_bpermute_b32 v195, v235, v193
	ds_bpermute_b32 v194, v235, v192
	v_xor_b32_e32 v235, 4, v202
	v_cmp_lt_i32_e32 vcc, v235, v228
	s_waitcnt lgkmcnt(0)
	v_pk_add_f32 v[192:193], v[192:193], v[194:195]
	v_cndmask_b32_e32 v235, v202, v235, vcc
	v_lshlrev_b32_e32 v235, 2, v235
	ds_bpermute_b32 v195, v235, v193
	ds_bpermute_b32 v194, v235, v192
	v_xor_b32_e32 v235, 2, v202
	v_cmp_lt_i32_e32 vcc, v235, v228
	s_waitcnt lgkmcnt(0)
	v_pk_add_f32 v[192:193], v[192:193], v[194:195]
	v_cndmask_b32_e32 v235, v202, v235, vcc
	v_lshlrev_b32_e32 v235, 2, v235
	ds_bpermute_b32 v195, v235, v193
	ds_bpermute_b32 v194, v235, v192
	v_xor_b32_e32 v235, 1, v202
	v_cmp_lt_i32_e32 vcc, v235, v228
	s_waitcnt lgkmcnt(0)
	v_pk_add_f32 v[192:193], v[192:193], v[194:195]
	v_cndmask_b32_e32 v228, v202, v235, vcc
	v_lshlrev_b32_e32 v228, 2, v228
	ds_bpermute_b32 v195, v228, v193
	ds_bpermute_b32 v194, v228, v192
	s_waitcnt lgkmcnt(0)
	v_pk_add_f32 v[192:193], v[192:193], v[194:195]
	s_nop 0
	v_pk_fma_f32 v[192:193], v[192:193], s[22:23], v[174:175] op_sel_hi:[1,0,0]
	s_nop 0
	v_mul_f32_e32 v228, 0x4b800000, v193
	v_cmp_gt_f32_e32 vcc, s56, v193
	v_mul_f32_e32 v235, 0x4b800000, v192
	v_cmp_gt_f32_e64 s[0:1], s56, v192
	v_cndmask_b32_e32 v228, v193, v228, vcc
	v_rsq_f32_e32 v228, v228
	v_cndmask_b32_e64 v235, v192, v235, s[0:1]
	v_rsq_f32_e32 v235, v235
	v_mul_f32_e32 v121, 0x45800000, v228
	v_cndmask_b32_e32 v228, v228, v121, vcc
	v_mul_f32_e32 v121, 0x45800000, v235
	v_mul_f32_e32 v228, v120, v228
	v_cndmask_b32_e64 v235, v235, v121, s[0:1]
	v_mul_f32_e32 v192, v120, v235
	v_pk_mul_f32 v[90:91], v[90:91], v[228:229] op_sel_hi:[1,0]
	v_pk_mul_f32 v[164:165], v[164:165], v[228:229] op_sel_hi:[1,0]
	s_waitcnt vmcnt(8)
; __device__ __forceinline__ void phase_norm(const Params& p, int mode, const u16* D, const float* gD, float scale,
;                            const float* gH, bool writeH) {
;     ...
; #pragma unroll
;       for (int i = 0; i < 4; ++i) {
;         xv[0][i].x += dv[0][i].x * r0 * g1[i].x; xv[0][i].y += dv[0][i].y * r0 * g1[i].y;
;         xv[0][i].z += dv[0][i].z * r0 * g1[i].z; xv[0][i].w += dv[0][i].w * r0 * g1[i].w;
;         xv[1][i].x += dv[1][i].x * r1 * g1[i].x; xv[1][i].y += dv[1][i].y * r1 * g1[i].y;
;         xv[1][i].z += dv[1][i].z * r1 * g1[i].z; xv[1][i].w += dv[1][i].w * r1 * g1[i].w;
;       }
;     }
; #pragma unroll
;     for (int r = 0; r < 2; ++r)
; #pragma unroll
;       for (int i = 0; i < 4; ++i) *(float4*)(p.x + (size_t)(row0 + r) * DM + i * 256 + lane * 4) = xv[r][i];
;     if (writeH) {
;       float ss0 = 0.f, ss1 = 0.f;
; #pragma unroll
;       for (int i = 0; i < 4; ++i) {
;         ss0 += xv[0][i].x * xv[0][i].x + xv[0][i].y * xv[0][i].y + xv[0][i].z * xv[0][i].z + xv[0][i].w * xv[0][i].w;
;         ss1 += xv[1][i].x * xv[1][i].x + xv[1][i].y * xv[1][i].y + xv[1][i].z * xv[1][i].z + xv[1][i].w * xv[1][i].w;
;       }
; #pragma unroll
;       for (int o = 32; o; o >>= 1) { ss0 += __shfl_xor(ss0, o); ss1 += __shfl_xor(ss1, o); }
	v_pk_fma_f32 v[134:135], v[206:207], v[90:91], v[134:135]
	v_pk_mul_f32 v[90:91], v[220:221], v[192:193] op_sel_hi:[1,0]
	v_pk_fma_f32 v[132:133], v[204:205], v[164:165], v[132:133]
	v_pk_fma_f32 v[148:149], v[204:205], v[90:91], v[148:149]
	v_pk_mul_f32 v[204:205], v[106:107], v[192:193] op_sel_hi:[1,0]
	s_nop 0
	v_pk_fma_f32 v[150:151], v[206:207], v[204:205], v[150:151]
	v_pk_mul_f32 v[204:205], v[166:167], v[228:229] op_sel_hi:[1,0]
	s_nop 0
	v_pk_fma_f32 v[136:137], v[208:209], v[204:205], v[136:137]
	v_pk_mul_f32 v[204:205], v[88:89], v[228:229] op_sel_hi:[1,0]
	s_nop 0
	v_pk_fma_f32 v[138:139], v[210:211], v[204:205], v[138:139]
	v_pk_mul_f32 v[204:205], v[222:223], v[192:193] op_sel_hi:[1,0]
	s_nop 0
	v_pk_fma_f32 v[152:153], v[208:209], v[204:205], v[152:153]
	v_pk_mul_f32 v[204:205], v[104:105], v[192:193] op_sel_hi:[1,0]
	s_nop 0
	v_pk_fma_f32 v[154:155], v[210:211], v[204:205], v[154:155]
	v_pk_mul_f32 v[204:205], v[168:169], v[228:229] op_sel_hi:[1,0]
	s_nop 0
	v_pk_fma_f32 v[140:141], v[212:213], v[204:205], v[140:141]
	v_pk_mul_f32 v[204:205], v[98:99], v[228:229] op_sel_hi:[1,0]
	s_nop 0
	v_pk_fma_f32 v[142:143], v[214:215], v[204:205], v[142:143]
	v_pk_mul_f32 v[204:205], v[224:225], v[192:193] op_sel_hi:[1,0]
	s_nop 0
	v_pk_fma_f32 v[156:157], v[212:213], v[204:205], v[156:157]
	v_pk_mul_f32 v[204:205], v[114:115], v[192:193] op_sel_hi:[1,0]
	s_nop 0
	v_pk_fma_f32 v[158:159], v[214:215], v[204:205], v[158:159]
	v_pk_mul_f32 v[204:205], v[170:171], v[228:229] op_sel_hi:[1,0]
	s_nop 0
	v_pk_fma_f32 v[144:145], v[216:217], v[204:205], v[144:145]
	v_pk_mul_f32 v[204:205], v[96:97], v[228:229] op_sel_hi:[1,0]
	s_nop 0
	v_pk_fma_f32 v[146:147], v[218:219], v[204:205], v[146:147]
	v_pk_mul_f32 v[204:205], v[226:227], v[192:193] op_sel_hi:[1,0]
	s_nop 0
	v_pk_fma_f32 v[160:161], v[216:217], v[204:205], v[160:161]
	v_pk_mul_f32 v[204:205], v[112:113], v[192:193] op_sel_hi:[1,0]
	s_nop 0
	v_pk_fma_f32 v[162:163], v[218:219], v[204:205], v[162:163]
.Ln529b:
	s_waitcnt vmcnt(8)
	v_lshl_add_u64 v[204:205], v[76:77], 0, v[240:241]
	global_store_dwordx4 v[204:205], v[132:135], off
	global_store_dwordx4 v[204:205], v[136:139], off offset:1024
	global_store_dwordx4 v[204:205], v[140:143], off offset:2048
	global_store_dwordx4 v[204:205], v[144:147], off offset:3072
	v_lshl_add_u64 v[204:205], v[76:77], 0, v[242:243]
	s_and_b64 vcc, exec, s[38:39]
	global_store_dwordx4 v[204:205], v[148:151], off
	global_store_dwordx4 v[204:205], v[152:155], off offset:1024
	global_store_dwordx4 v[204:205], v[156:159], off offset:2048
	global_store_dwordx4 v[204:205], v[160:163], off offset:3072
	s_cbranch_vccnz .Lnorm_latch2
	v_mov_b32_e32 v206, v133
	v_mov_b32_e32 v207, v137
	v_mov_b32_e32 v204, v132
	v_mov_b32_e32 v205, v136
	v_pk_mul_f32 v[206:207], v[206:207], v[206:207]
	v_mov_b32_e32 v208, v149
	v_pk_fma_f32 v[204:205], v[204:205], v[204:205], v[206:207]
	v_mov_b32_e32 v206, v134
	v_mov_b32_e32 v207, v138
	v_pk_fma_f32 v[204:205], v[206:207], v[206:207], v[204:205]
	v_mov_b32_e32 v206, v135
	v_mov_b32_e32 v207, v139
	v_mov_b32_e32 v209, v153
	v_pk_fma_f32 v[204:205], v[206:207], v[206:207], v[204:205]
	v_mov_b32_e32 v206, v148
	v_mov_b32_e32 v207, v152
	v_pk_mul_f32 v[208:209], v[208:209], v[208:209]
	v_mov_b32_e32 v210, v141
	v_pk_fma_f32 v[206:207], v[206:207], v[206:207], v[208:209]
	v_mov_b32_e32 v208, v150
	v_mov_b32_e32 v209, v154
	v_pk_fma_f32 v[206:207], v[208:209], v[208:209], v[206:207]
	v_mov_b32_e32 v208, v151
	v_mov_b32_e32 v209, v155
	v_mov_b32_e32 v211, v145
	v_pk_fma_f32 v[206:207], v[208:209], v[208:209], v[206:207]
	v_mov_b32_e32 v208, v140
	v_mov_b32_e32 v209, v144
	v_pk_mul_f32 v[210:211], v[210:211], v[210:211]
	v_mov_b32_e32 v212, v157
	v_pk_fma_f32 v[208:209], v[208:209], v[208:209], v[210:211]
	v_mov_b32_e32 v210, v142
	v_mov_b32_e32 v211, v146
	v_pk_fma_f32 v[208:209], v[210:211], v[210:211], v[208:209]
	v_mov_b32_e32 v210, v143
	v_mov_b32_e32 v211, v147
	v_mov_b32_e32 v213, v161
	v_pk_fma_f32 v[208:209], v[210:211], v[210:211], v[208:209]
	v_mov_b32_e32 v210, v156
	v_mov_b32_e32 v211, v160
	v_pk_mul_f32 v[212:213], v[212:213], v[212:213]
	v_and_b32_e32 v228, 64, v202
	v_pk_fma_f32 v[210:211], v[210:211], v[210:211], v[212:213]
	v_mov_b32_e32 v212, v158
	v_mov_b32_e32 v213, v162
	v_pk_fma_f32 v[210:211], v[212:213], v[212:213], v[210:211]
	v_mov_b32_e32 v212, v159
	v_mov_b32_e32 v213, v163
	v_pk_fma_f32 v[210:211], v[212:213], v[212:213], v[210:211]
	v_add_u32_e32 v228, 64, v228
	v_xor_b32_e32 v212, 32, v202
	v_cmp_lt_i32_e32 vcc, v212, v228
	v_mov_b32_e32 v213, v204
	v_mov_b32_e32 v204, v207
	v_cndmask_b32_e32 v212, v202, v212, vcc
	v_lshlrev_b32_e32 v214, 2, v212
	v_mov_b32_e32 v212, v206
	v_pk_add_f32 v[204:205], v[212:213], v[204:205]
	v_mov_b32_e32 v206, v210
	v_mov_b32_e32 v207, v208
	v_pk_add_f32 v[204:205], v[204:205], v[206:207]
	v_mov_b32_e32 v208, v211
	v_pk_add_f32 v[204:205], v[204:205], v[208:209]
	ds_bpermute_b32 v207, v214, v205
	ds_bpermute_b32 v206, v214, v204
	v_xor_b32_e32 v208, 16, v202
	v_cmp_lt_i32_e32 vcc, v208, v228
	s_waitcnt lgkmcnt(0)
; __device__ __forceinline__ void phase_norm(const Params& p, int mode, const u16* D, const float* gD, float scale,
;                            const float* gH, bool writeH) {
;     ...
;       for (int o = 32; o; o >>= 1) { ss0 += __shfl_xor(ss0, o); ss1 += __shfl_xor(ss1, o); }
;       const float rr[2] = {rsqrtf(ss0 * (1.0f / DM) + EPSN), rsqrtf(ss1 * (1.0f / DM) + EPSN)};
; #pragma unroll
;       for (int r = 0; r < 2; ++r)
; #pragma unroll
;         for (int i = 0; i < 4; ++i) {
;           uint2 o;
;           o.x = pack2bf(xv[r][i].x * rr[r] * g2[i].x, xv[r][i].y * rr[r] * g2[i].y);
;           o.y = pack2bf(xv[r][i].z * rr[r] * g2[i].z, xv[r][i].w * rr[r] * g2[i].w);
;           *(uint2*)(H + (size_t)(row0 + r) * DM + i * 256 + lane * 4) = o;
;         }
;     }
;   }
	v_pk_add_f32 v[204:205], v[204:205], v[206:207]
	v_cndmask_b32_e32 v208, v202, v208, vcc
	v_lshlrev_b32_e32 v208, 2, v208
	ds_bpermute_b32 v207, v208, v205
	ds_bpermute_b32 v206, v208, v204
	v_xor_b32_e32 v208, 8, v202
	v_cmp_lt_i32_e32 vcc, v208, v228
	s_waitcnt lgkmcnt(0)
	v_pk_add_f32 v[204:205], v[204:205], v[206:207]
	v_cndmask_b32_e32 v208, v202, v208, vcc
	v_lshlrev_b32_e32 v208, 2, v208
	ds_bpermute_b32 v207, v208, v205
	ds_bpermute_b32 v206, v208, v204
	v_xor_b32_e32 v208, 4, v202
	v_cmp_lt_i32_e32 vcc, v208, v228
	s_waitcnt lgkmcnt(0)
	v_pk_add_f32 v[204:205], v[204:205], v[206:207]
	v_cndmask_b32_e32 v208, v202, v208, vcc
	v_lshlrev_b32_e32 v208, 2, v208
	ds_bpermute_b32 v207, v208, v205
	ds_bpermute_b32 v206, v208, v204
	v_xor_b32_e32 v208, 2, v202
	v_cmp_lt_i32_e32 vcc, v208, v228
	s_waitcnt lgkmcnt(0)
	v_pk_add_f32 v[204:205], v[204:205], v[206:207]
	v_cndmask_b32_e32 v208, v202, v208, vcc
	v_lshlrev_b32_e32 v208, 2, v208
	ds_bpermute_b32 v207, v208, v205
	ds_bpermute_b32 v206, v208, v204
	v_xor_b32_e32 v208, 1, v202
	v_cmp_lt_i32_e32 vcc, v208, v228
	s_waitcnt lgkmcnt(0)
	v_pk_add_f32 v[204:205], v[204:205], v[206:207]
	v_cndmask_b32_e32 v228, v202, v208, vcc
	v_lshlrev_b32_e32 v228, 2, v228
	ds_bpermute_b32 v207, v228, v205
	ds_bpermute_b32 v206, v228, v204
	s_waitcnt lgkmcnt(0)
	v_pk_add_f32 v[204:205], v[204:205], v[206:207]
	s_nop 0
	v_pk_fma_f32 v[204:205], v[204:205], s[22:23], v[174:175] op_sel_hi:[1,0,0]
	v_lshl_add_u64 v[206:207], v[74:75], 0, v[236:237]
	v_mul_f32_e32 v228, 0x4b800000, v205
	v_cmp_gt_f32_e32 vcc, s56, v205
	v_cmp_gt_f32_e64 s[0:1], s56, v204
	s_nop 0
	v_cndmask_b32_e32 v228, v205, v228, vcc
	v_rsq_f32_e32 v228, v228
	v_mul_f32_e32 v205, 0x4b800000, v204
	v_cndmask_b32_e64 v204, v204, v205, s[0:1]
	v_rsq_f32_e32 v204, v204
	v_mul_f32_e32 v205, 0x45800000, v228
	v_cndmask_b32_e32 v228, v228, v205, vcc
	v_pk_mul_f32 v[132:133], v[132:133], v[228:229] op_sel_hi:[1,0]
	v_pk_mul_f32 v[134:135], v[134:135], v[228:229] op_sel_hi:[1,0]
	v_pk_mul_f32 v[132:133], v[176:177], v[132:133]
	v_pk_mul_f32 v[134:135], v[178:179], v[134:135]
	v_cvt_pk_bf16_f32 v132, v132, v133
	v_cvt_pk_bf16_f32 v133, v134, v135
	global_store_dwordx2 v[206:207], v[132:133], off
	v_pk_mul_f32 v[132:133], v[136:137], v[228:229] op_sel_hi:[1,0]
	v_pk_mul_f32 v[134:135], v[138:139], v[228:229] op_sel_hi:[1,0]
	v_pk_mul_f32 v[132:133], v[180:181], v[132:133]
	v_pk_mul_f32 v[134:135], v[182:183], v[134:135]
	v_cvt_pk_bf16_f32 v132, v132, v133
	v_cvt_pk_bf16_f32 v133, v134, v135
	global_store_dwordx2 v[206:207], v[132:133], off offset:512
	v_pk_mul_f32 v[132:133], v[140:141], v[228:229] op_sel_hi:[1,0]
	v_pk_mul_f32 v[134:135], v[142:143], v[228:229] op_sel_hi:[1,0]
	v_pk_mul_f32 v[132:133], v[184:185], v[132:133]
	v_pk_mul_f32 v[134:135], v[186:187], v[134:135]
	v_cvt_pk_bf16_f32 v132, v132, v133
	v_cvt_pk_bf16_f32 v133, v134, v135
	v_mul_f32_e32 v205, 0x45800000, v204
	global_store_dwordx2 v[206:207], v[132:133], off offset:1024
	v_pk_mul_f32 v[132:133], v[144:145], v[228:229] op_sel_hi:[1,0]
	v_pk_mul_f32 v[134:135], v[146:147], v[228:229] op_sel_hi:[1,0]
	v_cndmask_b32_e64 v204, v204, v205, s[0:1]
	v_pk_mul_f32 v[132:133], v[188:189], v[132:133]
	v_pk_mul_f32 v[134:135], v[190:191], v[134:135]
	v_cvt_pk_bf16_f32 v132, v132, v133
	v_cvt_pk_bf16_f32 v133, v134, v135
	v_pk_mul_f32 v[134:135], v[148:149], v[204:205] op_sel_hi:[1,0]
	v_pk_mul_f32 v[136:137], v[150:151], v[204:205] op_sel_hi:[1,0]
	v_pk_mul_f32 v[134:135], v[176:177], v[134:135]
	v_pk_mul_f32 v[136:137], v[178:179], v[136:137]
	global_store_dwordx2 v[206:207], v[132:133], off offset:1536
	v_lshl_add_u64 v[132:133], v[74:75], 0, v[238:239]
	v_cvt_pk_bf16_f32 v134, v134, v135
	v_cvt_pk_bf16_f32 v135, v136, v137
	global_store_dwordx2 v[132:133], v[134:135], off
	v_pk_mul_f32 v[134:135], v[152:153], v[204:205] op_sel_hi:[1,0]
	v_pk_mul_f32 v[136:137], v[154:155], v[204:205] op_sel_hi:[1,0]
	v_pk_mul_f32 v[134:135], v[180:181], v[134:135]
	v_pk_mul_f32 v[136:137], v[182:183], v[136:137]
	v_cvt_pk_bf16_f32 v134, v134, v135
	v_cvt_pk_bf16_f32 v135, v136, v137
	global_store_dwordx2 v[132:133], v[134:135], off offset:512
	v_pk_mul_f32 v[134:135], v[156:157], v[204:205] op_sel_hi:[1,0]
	v_pk_mul_f32 v[136:137], v[158:159], v[204:205] op_sel_hi:[1,0]
	v_pk_mul_f32 v[134:135], v[184:185], v[134:135]
	v_pk_mul_f32 v[136:137], v[186:187], v[136:137]
	v_cvt_pk_bf16_f32 v134, v134, v135
	v_cvt_pk_bf16_f32 v135, v136, v137
	global_store_dwordx2 v[132:133], v[134:135], off offset:1024
	v_pk_mul_f32 v[134:135], v[160:161], v[204:205] op_sel_hi:[1,0]
	v_pk_mul_f32 v[136:137], v[162:163], v[204:205] op_sel_hi:[1,0]
	v_pk_mul_f32 v[134:135], v[188:189], v[134:135]
	v_pk_mul_f32 v[136:137], v[190:191], v[136:137]
	v_cvt_pk_bf16_f32 v134, v134, v135
	v_cvt_pk_bf16_f32 v135, v136, v137
	global_store_dwordx2 v[132:133], v[134:135], off offset:1536
	s_branch .Lnorm_latch2
.Lnorm_latch2:
	s_add_i32 s10, s10, s96
	s_add_i32 s10, s10, s96
	v_add_u32_e32 v78, s11, v78
	v_add_u32_e32 v78, s11, v78
	s_cmpk_lt_i32 s10, 0x800
	s_cbranch_scc1 .LBB0_495
	s_branch .LBB0_531
